# H3: XOR-swizzle of the gate (GST) and output (YST) LDS tiles: 16-B chunk index ^ 2*((row>>2)&3) so the 16-bit accesses of step 5 are bank-conflict-free (was 4-way); on top of v065
# baseline (speedup 1.0000x reference)
; __device__ __forceinline__ float sigmoidf_(float x) { return __builtin_amdgcn_rcpf(1.f + __expf(-x)); }
; __device__ __forceinline__ unsigned short bf1(float x) { unsigned r; asm("v_cvt_pk_bf16_f32 %0, %1, %1" : "=v"(r) : "v"(x)); return (unsigned short)r; }
; __device__ __forceinline__ void h3_phase(const Ptrs& P, LAS unsigned char* lds, int bx, int G, int tid) {
;     ...
;     const int d = tid & 127, i = __builtin_amdgcn_readfirstlane(tid >> 7), lane = tid & 63, w = __builtin_amdgcn_readfirstlane(tid >> 6);
;     const int fr = lane & 15, fq = lane >> 4;
;     const int NIT = NCH * NH;
;     if (bx >= NIT) return;
;     h16x8 pf[2], pq[2], pv[2], pg[2]; bf16x8 psb[4];
;     ...
;     H3_PREFETCH(bx);
;     const bool hfix = (G & 15) == 0;
;     float l0 = P.lb_logits[(bx & 15) * HD + d], l1 = P.lb_logits[HW + (bx & 15) * HD + d], nwv = P.hgrn_nw[16 * w + fr];
;     size_t yoff = 0; bool have_y = false;
;     ...
;     for (int it = bx; it < NIT; it += G) {
;     ...
;             for (int jj = 0; jj < 4; ++jj) { const int t = 16 * m + 4 * fq + jj; const float ss = red[t];
;                 const float rs = rsqrtf(ss * (1.f / HD) + EPS);
;                 const float gv = (float)GST[t * 128 + e];
;                 const float yv = o[m][jj] * rs * nwv * gv * sigmoidf_(gv);
;     ...
;                 YST[t * 128 + e] = bf1(yv);
;     ...
;                 YST[t * 128 + e] = __builtin_bit_cast(unsigned short, (h16)yv);
.LBB0_350:
	s_or_b64 exec, exec, s[0:1]
	s_add_i32 s0, 0, 0x24018
	s_waitcnt lgkmcnt(0)
	v_mov_b32_e32 v0, s0
	s_add_i32 s0, 0, 0x24060
	s_barrier
	ds_read2_b64 v[0:3], v0 offset1:1
	v_mov_b32_e32 v4, s0
	ds_read_b64 v[4:5], v4
	s_and_b64 vcc, exec, s[4:5]
	s_waitcnt lgkmcnt(1)
	v_readfirstlane_b32 s45, v1
	v_readfirstlane_b32 s44, v0
	v_mbcnt_lo_u32_b32 v1, -1, 0
	v_mbcnt_hi_u32_b32 v1, -1, v1
	v_readfirstlane_b32 s1, v3
	v_or_b32_e32 v0, s33, v1
	v_readfirstlane_b32 s0, v2
	s_waitcnt lgkmcnt(0)
	v_readfirstlane_b32 s7, v5
	v_readfirstlane_b32 s8, v4
	v_readfirstlane_b32 s6, v0
	s_cbranch_vccz .LBB0_405
	s_add_u32 s68, s8, 0x14200000
	s_addc_u32 s69, s7, 0
	s_add_u32 s66, s8, 0x28200000
	s_addc_u32 s67, s7, 0
	s_ashr_i32 s70, s6, 6
	s_add_u32 s56, s8, 0x30200000
	s_addc_u32 s57, s7, 0
	s_lshl_b32 s8, s2, 2
	v_and_b32_e32 v79, 15, v1
	s_andn2_b32 s8, s8, 63
	s_lshl_b32 s7, s2, 7
	s_ashr_i32 s9, s8, 31
	v_lshl_or_b32 v76, s70, 4, v79
	s_lshl_b64 s[4:5], s[2:3], 15
	s_and_b32 s7, s7, 0x780
	s_lshl_b64 s[8:9], s[8:9], 14
	s_ashr_i32 s72, s6, 7
	v_ashrrev_i32_e32 v77, 31, v76
	v_lshl_add_u64 v[6:7], v[76:77], 2, s[0:1]
	s_add_u32 s0, s68, s8
	v_lshlrev_b32_e32 v62, 3, v0
	s_addc_u32 s1, s69, s9
	s_lshl_b32 s8, s7, 1
	v_and_b32_e32 v70, 0x78, v62
	v_add_u32_e32 v4, 0x200, v0
	s_add_u32 s0, s0, s8
	v_mov_b32_e32 v69, 0
	v_ashrrev_i32_e32 v52, 4, v4
	v_lshlrev_b32_e32 v4, 7, v76
	s_addc_u32 s1, s1, 0
	v_lshlrev_b32_e32 v68, 1, v70
	v_ashrrev_i32_e32 v2, 4, v0
	v_ashrrev_i32_e32 v5, 31, v4
	v_lshl_add_u64 v[20:21], s[0:1], 0, v[68:69]
	s_add_u32 s0, s56, s4
	v_bfe_u32 v1, v1, 4, 2
	v_ashrrev_i32_e32 v3, 31, v2
	s_mov_b64 s[46:47], 0x2000
	s_addc_u32 s1, s57, s5
	v_lshlrev_b64 v[54:55], 1, v[4:5]
	v_lshlrev_b64 v[72:73], 14, v[2:3]
	v_ashrrev_i32_e32 v53, 31, v52
	global_load_dword v77, v[6:7], off
	v_lshl_add_u64 v[6:7], v[20:21], 0, s[46:47]
	v_lshl_add_u64 v[4:5], s[0:1], 0, v[54:55]
	v_lshlrev_b32_e32 v56, 4, v1
	v_mov_b32_e32 v57, v69
	v_lshlrev_b64 v[74:75], 14, v[52:53]
	v_lshl_add_u64 v[8:9], v[6:7], 0, v[72:73]
	v_lshl_add_u64 v[4:5], v[4:5], 0, v[56:57]
	s_mov_b64 s[48:49], 0x3000
	v_lshl_add_u64 v[6:7], v[6:7], 0, v[74:75]
	global_load_dwordx4 v[16:19], v[8:9], off
	global_load_dwordx4 v[12:15], v[6:7], off
	global_load_dwordx4 v[36:39], v[4:5], off offset:192
	global_load_dwordx4 v[40:43], v[4:5], off offset:128
	global_load_dwordx4 v[44:47], v[4:5], off offset:64
	global_load_dwordx4 v[48:51], v[4:5], off
	v_lshl_add_u64 v[4:5], v[20:21], 0, s[48:49]
	v_lshl_add_u64 v[22:23], v[4:5], 0, v[74:75]
	s_mov_b64 s[50:51], 0x1000
	v_lshl_add_u64 v[24:25], v[4:5], 0, v[72:73]
	global_load_dwordx4 v[4:7], v[22:23], off
	global_load_dwordx4 v[8:11], v[24:25], off
	v_lshl_add_u64 v[22:23], v[20:21], 0, s[50:51]
	v_and_b32_e32 v71, 0x7f, v0
	v_lshl_add_u64 v[24:25], v[22:23], 0, v[74:75]
	v_lshl_add_u64 v[22:23], v[22:23], 0, v[72:73]
	v_lshl_add_u64 v[58:59], v[20:21], 0, v[74:75]
	global_load_dwordx4 v[28:31], v[24:25], off
	global_load_dwordx4 v[32:35], v[22:23], off
	v_lshl_add_u64 v[60:61], v[20:21], 0, v[72:73]
	global_load_dwordx4 v[20:23], v[58:59], off
	global_load_dwordx4 v[24:27], v[60:61], off
	v_or_b32_e32 v58, s7, v71
	s_add_i32 s0, 0, 0x19e00
	v_lshlrev_b32_e32 v58, 2, v58
	v_mov_b32_e32 v59, v69
	v_lshl_add_u32 v86, v71, 2, s0
	v_lshl_add_u64 v[60:61], s[44:45], 0, v[58:59]
	s_movk_i32 s0, 0x2000
	v_add_co_u32_e32 v60, vcc, s0, v60
	v_lshlrev_b32_e32 v63, 3, v1
	s_nop 0
	v_addc_co_u32_e32 v61, vcc, 0, v61, vcc
	global_load_dword v90, v[60:61], off
	global_load_dword v89, v58, s[44:45]
	v_lshlrev_b32_e32 v95, 2, v1
	v_lshlrev_b32_e32 v250, 3, v95
	v_lshlrev_b32_e32 v1, 9, v1
	s_add_i32 s59, 0, 0x1ae00
	s_add_i32 s60, 0, 0x1ee00
	v_or_b32_e32 v116, 1, v95
	v_add_lshl_u32 v1, v76, v1, 1
	v_xor_b32_e32 v1, v250, v1
	v_add_u32_e32 v122, s59, v1
	v_add_u32_e32 v123, s60, v1
	v_lshlrev_b32_e32 v1, 7, v116
	v_or_b32_e32 v117, 2, v95
	v_add_lshl_u32 v1, v1, v76, 1
	v_xor_b32_e32 v1, v250, v1
	v_add_u32_e32 v125, s59, v1
	v_add_u32_e32 v126, s60, v1
	v_lshlrev_b32_e32 v1, 7, v117
	v_or_b32_e32 v118, 3, v95
	v_add_lshl_u32 v1, v1, v76, 1
	v_xor_b32_e32 v1, v250, v1
	v_add_u32_e32 v128, s59, v1
	v_add_u32_e32 v129, s60, v1
	v_lshlrev_b32_e32 v1, 7, v118
	v_add_lshl_u32 v1, v1, v76, 1
	v_xor_b32_e32 v1, v250, v1
	s_add_i32 s58, 0, 0x1a600
	v_add_u32_e32 v131, s59, v1
	v_add_u32_e32 v132, s60, v1
	v_or_b32_e32 v1, 16, v95
	v_lshl_add_u32 v133, v1, 2, s58
	v_lshlrev_b32_e32 v1, 7, v1
	v_add_lshl_u32 v1, v1, v76, 1
	v_xor_b32_e32 v1, v250, v1
	v_add_u32_e32 v134, s59, v1
	v_add_u32_e32 v135, s60, v1
	v_or_b32_e32 v1, 17, v95
	v_lshl_add_u32 v136, v1, 2, s58
	v_lshlrev_b32_e32 v1, 7, v1
	v_add_lshl_u32 v1, v1, v76, 1
	v_xor_b32_e32 v1, v250, v1
	v_add_u32_e32 v137, s59, v1
	v_add_u32_e32 v138, s60, v1
	v_or_b32_e32 v1, 18, v95
	v_lshl_add_u32 v139, v1, 2, s58
	v_lshlrev_b32_e32 v1, 7, v1
	v_add_lshl_u32 v1, v1, v76, 1
	v_xor_b32_e32 v1, v250, v1
	s_add_i32 s7, 0, 0x15600
	s_and_b32 s0, s6, 0x3fffff80
	s_lshl_b32 s22, s72, 4
	v_add_u32_e32 v140, s59, v1
	v_add_u32_e32 v141, s60, v1
	v_or_b32_e32 v1, 19, v95
	s_cmp_lt_i32 s70, 10
	v_lshl_add_u32 v142, v1, 2, s58
	v_lshlrev_b32_e32 v1, 7, v1
	s_cselect_b64 s[52:53], -1, 0
	s_add_i32 s61, 0, 0x13200
	v_add_lshl_u32 v1, v1, v76, 1
	v_xor_b32_e32 v1, v250, v1
	s_movk_i32 s8, 0x90
; __device__ __forceinline__ float sigmoidf_(float x) { return __builtin_amdgcn_rcpf(1.f + __expf(-x)); }
; __device__ __forceinline__ unsigned short bf1(float x) { unsigned r; asm("v_cvt_pk_bf16_f32 %0, %1, %1" : "=v"(r) : "v"(x)); return (unsigned short)r; }
; __device__ __forceinline__ void h3_phase(const Ptrs& P, LAS unsigned char* lds, int bx, int G, int tid) {
;     ...
;         const int e = 16 * w + fr;
; #pragma unroll
;         for (int m = 0; m < 4; ++m)
; #pragma unroll
;             for (int jj = 0; jj < 4; ++jj) { const int t = 16 * m + 4 * fq + jj; const float ss = red[t];
;                 const float rs = rsqrtf(ss * (1.f / HD) + EPS);
;                 const float gv = (float)GST[t * 128 + e];
;                 const float yv = o[m][jj] * rs * nwv * gv * sigmoidf_(gv);
;     ...
;                 YST[t * 128 + e] = bf1(yv);
;     ...
;                 YST[t * 128 + e] = __builtin_bit_cast(unsigned short, (h16)yv);
	s_cmp_gt_i32 s72, 0
	v_add_u32_e32 v143, s59, v1
	v_add_u32_e32 v144, s60, v1
	v_or_b32_e32 v1, 32, v95
	v_mul_lo_u32 v64, v76, s8
	s_cselect_b64 s[8:9], -1, 0
	s_cmp_lt_i32 s72, 1
	v_lshl_add_u32 v145, v1, 2, s58
	v_lshlrev_b32_e32 v1, 7, v1
	s_cselect_b64 s[10:11], -1, 0
	s_cmp_gt_i32 s72, 1
	v_add_lshl_u32 v1, v1, v76, 1
	v_xor_b32_e32 v1, v250, v1
	s_cselect_b64 s[12:13], -1, 0
	s_cmp_lt_i32 s72, 2
	v_add_u32_e32 v146, s59, v1
	v_add_u32_e32 v147, s60, v1
	v_or_b32_e32 v1, 33, v95
	s_cselect_b64 s[14:15], -1, 0
	s_cmp_gt_i32 s72, 2
	v_lshl_add_u32 v148, v1, 2, s58
	v_lshlrev_b32_e32 v1, 7, v1
	s_cselect_b64 s[16:17], -1, 0
	s_cmp_lt_i32 s72, 3
	v_add_lshl_u32 v1, v1, v76, 1
	v_xor_b32_e32 v1, v250, v1
	v_lshlrev_b32_e32 v58, 4, v0
	s_cselect_b64 s[18:19], -1, 0
	s_cmp_gt_i32 s72, 3
	v_add_u32_e32 v149, s59, v1
	v_add_u32_e32 v150, s60, v1
	v_or_b32_e32 v1, 34, v95
	v_and_b32_e32 v59, 0xffffff00, v58
	s_cselect_b64 s[20:21], -1, 0
	s_cmp_lt_i32 s72, 4
	v_lshl_add_u32 v151, v1, 2, s58
	v_lshlrev_b32_e32 v1, 7, v1
	v_add3_u32 v87, 0, v68, v59
	v_lshrrev_b32_e32 v251, 1, v0
	v_and_b32_e32 v251, 0x60, v251
	v_xor_b32_e32 v251, v251, v68
	v_add3_u32 v93, s59, v251, v59
	v_lshlrev_b32_e32 v59, 1, v71
	s_cselect_b64 s[54:55], -1, 0
	s_or_b32 s22, s22, 1
	v_add_lshl_u32 v1, v1, v76, 1
	v_xor_b32_e32 v1, v250, v1
	v_add_u32_e32 v94, 0, v59
	v_lshl_or_b32 v59, s72, 12, v59
	s_mul_i32 s23, s72, 0x880
	s_mulk_i32 s22, 0x110
	v_add_u32_e32 v152, s59, v1
	v_add_u32_e32 v153, s60, v1
	v_or_b32_e32 v1, 35, v95
	v_add_u32_e32 v97, 0, v59
	v_or_b32_e32 v59, s23, v71
	s_add_i32 s23, s22, 0x110
	v_lshl_add_u32 v154, v1, 2, s58
	v_lshlrev_b32_e32 v1, 7, v1
	v_or_b32_e32 v66, 48, v95
	v_add_u32_e32 v100, s23, v94
	s_add_i32 s23, s22, 0x220
	v_add_lshl_u32 v1, v1, v76, 1
	v_xor_b32_e32 v1, v250, v1
	v_add_u32_e32 v101, s23, v94
	s_add_i32 s23, s22, 0x330
	v_add_u32_e32 v155, s59, v1
	v_add_u32_e32 v156, s60, v1
	v_lshlrev_b32_e32 v1, 7, v66
	v_add_u32_e32 v102, s23, v94
	s_add_i32 s23, s22, 0x440
	v_add_lshl_u32 v1, v1, v76, 1
	v_xor_b32_e32 v1, v250, v1
	v_add_u32_e32 v103, s23, v94
	s_add_i32 s23, s22, 0x550
	v_add_u32_e32 v157, s59, v1
	v_add_u32_e32 v158, s60, v1
	v_or_b32_e32 v1, 49, v95
	v_add_u32_e32 v104, s23, v94
	s_add_i32 s23, s22, 0x660
	v_lshl_add_u32 v159, v1, 2, s58
	v_lshlrev_b32_e32 v1, 7, v1
	v_add_u32_e32 v105, s23, v94
	s_add_i32 s23, s22, 0x770
	v_add_lshl_u32 v1, v1, v76, 1
	v_xor_b32_e32 v1, v250, v1
	v_add_u32_e32 v106, s23, v94
	s_add_i32 s23, s22, 0x880
	v_add_u32_e32 v160, s59, v1
	v_add_u32_e32 v161, s60, v1
	v_or_b32_e32 v1, 50, v95
	v_bitop3_b32 v60, v62, v2, 56 bitop3:0x6c
	v_add_u32_e32 v64, s7, v64
	v_add_u32_e32 v108, s23, v94
	s_add_i32 s23, s22, 0x990
	v_lshlrev_b32_e32 v113, 8, v2
	v_lshlrev_b64 v[82:83], 13, v[2:3]
	v_bitop3_b32 v2, v76, v63, 56 bitop3:0x6c
	v_lshl_add_u32 v162, v1, 2, s58
	v_lshlrev_b32_e32 v1, 7, v1
	v_add_u32_e32 v109, s23, v94
	s_add_i32 s23, s22, 0xaa0
	v_lshl_add_u32 v119, v2, 1, v64
	v_or_b32_e32 v2, 32, v63
	v_add_lshl_u32 v1, v1, v76, 1
	v_xor_b32_e32 v1, v250, v1
	v_add_u32_e32 v110, s23, v94
	s_add_i32 s23, s22, 0xbb0
	v_bitop3_b32 v2, v76, v2, 56 bitop3:0x6c
	v_add_u32_e32 v163, s59, v1
	v_add_u32_e32 v164, s60, v1
	v_or_b32_e32 v1, 51, v95
	v_bitop3_b32 v62, v52, v62, 56 bitop3:0x78
	v_add_u32_e32 v111, s23, v94
	s_add_i32 s23, s22, 0xcc0
	v_lshl_add_u32 v120, v2, 1, v64
	v_lshl_add_u32 v165, v1, 2, s58
	v_lshlrev_b32_e32 v1, 7, v1
	v_lshl_add_u64 v[2:3], s[56:57], 0, v[54:55]
	s_lshl_b32 s56, s70, 5
	v_lshl_add_u32 v60, v60, 1, s7
	v_mul_u32_u24_e32 v61, 0x90, v70
	v_lshl_add_u32 v62, v62, 1, s7
	v_lshl_add_u32 v91, s0, 2, v86
	s_movk_i32 s0, 0x240
	v_add_u32_e32 v78, 0, v56
	v_add_u32_e32 v65, s61, v56
	v_add_u32_e32 v99, s22, v94
	v_add_u32_e32 v112, s23, v94
	s_add_i32 s23, s22, 0xdd0
	s_addk_i32 s22, 0xee0
	v_lshlrev_b32_e32 v107, 8, v52
	v_lshlrev_b64 v[80:81], 13, v[52:53]
	v_mul_u32_u24_e32 v52, 0x110, v79
	v_mul_u32_u24_e32 v53, 0x90, v79
	v_add_lshl_u32 v1, v1, v76, 1
	v_xor_b32_e32 v1, v250, v1
	v_add_u32_e32 v169, s61, v58
	s_add_i32 s61, s61, s56
	v_cmp_gt_i32_e64 s[0:1], s0, v0
	v_cmp_gt_i32_e64 s[4:5], 64, v0
	v_lshl_add_u32 v92, v0, 2, s58
	v_lshrrev_b32_e32 v251, 1, v0
	v_and_b32_e32 v251, 0x60, v251
	v_xor_b32_e32 v251, v251, v68
	v_add_u32_e32 v88, s60, v251
	v_cmp_eq_u32_e64 s[6:7], 0, v79
	v_lshl_add_u32 v96, v66, 2, s58
	v_lshl_add_u32 v98, v59, 1, 0
	s_movk_i32 s71, 0x110
	v_add_u32_e32 v114, s23, v94
	v_add_u32_e32 v115, s22, v94
	s_mulk_i32 s72, 0x1100
	v_cmp_gt_u32_e64 s[22:23], v79, v95
	v_cmp_gt_u32_e64 s[24:25], v79, v116
	v_cmp_gt_u32_e64 s[26:27], v79, v117
	v_cmp_gt_u32_e64 s[28:29], v79, v118
	v_add_u32_e32 v121, s58, v56
	v_lshl_add_u32 v124, v116, 2, s58
	v_lshl_add_u32 v127, v117, 2, s58
	v_lshl_add_u32 v130, v118, 2, s58
	v_add_u32_e32 v166, s59, v1
	v_add_u32_e32 v167, s60, v1
	v_lshl_add_u64 v[84:85], v[2:3], 0, v[56:57]
	v_add_u32_e32 v168, 0xfffffe00, v0
	v_lshl_add_u32 v170, v79, 1, s61
	s_mov_b64 s[60:61], 0
	s_mov_b64 s[58:59], 0
	v_add_u32_e32 v171, v60, v61
	v_add_u32_e32 v172, v62, v61
	v_add_u32_e32 v173, v78, v52
	v_add_u32_e32 v174, v65, v53
	v_mov_b32_e32 v175, 0x358637bd
	s_mov_b32 s73, 0x800000
	v_mov_b32_e32 v0, v69
	v_mov_b32_e32 v1, v69
	v_mov_b32_e32 v2, v69
	v_mov_b32_e32 v3, v69
	s_mov_b32 s75, s2
	s_branch .LBB0_353
